# lru_chunk0 sweep: c8=-8*softplus(-ap) hoisted to once per unit via LDS table (ba/bx too), gate weights register-prefetched one g-iteration ahead
# speedup vs baseline: 1.0109x; 1.0109x over previous
; __device__ __forceinline__ int ltid(int wv) { int l; asm volatile("v_mbcnt_lo_u32_b32 %0, -1, 0\n\tv_mbcnt_hi_u32_b32 %0, -1, %0" : "=v"(l)); asm volatile("" : "+s"(wv)); return (wv << 6) | l; }
; #define LAS __attribute__((address_space(3)))
; DI float softplus_f(float x) { return x > 20.f ? x : log1pf(__expf(x)); }
; DI u32x4 pack8(const float (&v)[8]) { u32x4 w; w.x = pk2(v[0], v[1]); w.y = pk2(v[2], v[3]); w.z = pk2(v[4], v[5]); w.w = pk2(v[6], v[7]); return w; }
; template <bool OUT>
; DI void lru_sweep(LAS bf16_t* U, LAS float* SUM, const Args& a, const LayerP& P, int row0, int wv, const float* LC, f32x2* LSWc) {
;     ...
;         bf16x8 af[2];
; #pragma unroll
;         for (int ks = 0; ks < 2; ++ks) af[ks] = *(const LAS bf16x8*)(U + (l0 + r) * PU + g * 64 + ks * 32 + q * 8);
; #pragma unroll
;         for (int ni = 0; ni < 4; ++ni) { f32x4 aa1 = (f32x4){0.f, 0.f, 0.f, 0.f}, ax1 = aa1;
; #pragma unroll
;             for (int ks = 0; ks < 2; ++ks) { const bf16x8 wa = *(const bf16x8*)(LWT + ((size_t)(g * 64 + ni * 16 + r)) * 64 + ks * 32 + q * 8), wx = *(const bf16x8*)(LWT + ((size_t)((4 + g) * 64 + ni * 16 + r)) * 64 + ks * 32 + q * 8);
;                 aa1 = __builtin_amdgcn_mfma_f32_16x16x32_bf16(af[ks], wa, aa1, 0, 0, 0); ax1 = __builtin_amdgcn_mfma_f32_16x16x32_bf16(af[ks], wx, ax1, 0, 0, 0); }
;             const int ch = g * 64 + ni * 16 + r; const float ba = P.lru_ba[ch], bx = P.lru_bx[ch], c8 = -8.0f * softplus_f(-P.lru_ap[ch]);
; template <int MODE>
; DI void lru_chunk(LAS unsigned char* lds, const Args& a, const LayerP& P, int unit, int wv) {
;     const int tid = ltid(wv), c = unit & (NCH - 1), b = unit >> 7, row0 = b * SEQ + c * 128;
;     LAS bf16_t* U = (LAS bf16_t*)lds; LAS float* SUM = (LAS float*)(lds + 67584);
;     const bf16_t* Hb = (const bf16_t*)(a.ws + WS_H) + (size_t)b * SEQ * HP;
;     __syncthreads();
;     { const int cv = tid & 31, run = tid >> 5;
; #pragma unroll
;       for (int hf = 0; hf < 2; ++hf) { const int t0 = run * 8 + hf * 4; float o[4][8]; conv8x4<false>(Hb + C_LX + cv * 8, c * 128 + t0, P.lru_cw + cv * 8, 256, P.lru_cb + cv * 8, o);
; #pragma unroll
;           for (int t = 0; t < 4; ++t) *(LAS u32x4*)(U + (t0 + t) * PU + cv * 8) = pack8(o[t]); } }
;     __syncthreads();
.LBB0_1004:
	s_mov_b32 s2, s77
	v_mbcnt_lo_u32_b32 v0, -1, 0
	v_mbcnt_hi_u32_b32 v0, -1, v0
	s_ashr_i32 s16, s18, 7
	v_lshl_or_b32 v72, s2, 6, v0
	s_lshl_b32 s2, s18, 7
	s_and_b32 s15, s2, 0x3f80
	s_mul_i32 s2, s16, 0x6000000
	v_lshlrev_b32_e32 v0, 3, v0
	s_mul_hi_i32 s3, s16, 0x6000000
	s_add_u32 s2, s20, s2
	v_ashrrev_i32_e32 v73, 2, v72
	v_and_b32_e32 v2, 0xf8, v0
	s_addc_u32 s3, s21, s3
	v_and_b32_e32 v43, -8, v73
	v_lshlrev_b32_e32 v0, 1, v2
	v_lshl_add_u64 v[4:5], s[2:3], 0, v[0:1]
	s_mov_b64 s[2:3], 0x6801320
	v_add_u32_e32 v0, s15, v43
	v_lshl_add_u64 v[74:75], v[4:5], 0, s[2:3]
	v_cmp_lt_i32_e32 vcc, 2, v0
	v_mov_b32_e32 v52, 0
	v_mov_b32_e32 v60, 0
	v_mov_b32_e32 v61, 0
	v_mov_b32_e32 v62, 0
	v_mov_b32_e32 v63, 0
	s_barrier
	v_and_b32_e32 v178, 0xff, v72
	v_lshlrev_b32_e32 v178, 2, v178
	global_load_dword v175, v178, s[38:39]
	global_load_dword v176, v178, s[26:27]
	global_load_dword v177, v178, s[36:37]
	v_and_b32_e32 v173, 15, v72
	v_bfe_u32 v174, v72, 4, 2
	v_lshlrev_b32_e32 v173, 7, v173
	v_lshl_add_u32 v173, v174, 4, v173
	v_add_u32_e32 v174, 0x1000, v173
	s_add_u32 s46, s48, 0x8000
	s_addc_u32 s47, s49, 0
	global_load_dwordx4 v[108:111], v173, s[48:49]
	global_load_dwordx4 v[112:115], v173, s[46:47]
	global_load_dwordx4 v[116:119], v173, s[48:49] offset:64
	global_load_dwordx4 v[120:123], v173, s[46:47] offset:64
	global_load_dwordx4 v[124:127], v173, s[48:49] offset:2048
	global_load_dwordx4 v[128:131], v173, s[46:47] offset:2048
	global_load_dwordx4 v[132:135], v173, s[48:49] offset:2112
	global_load_dwordx4 v[136:139], v173, s[46:47] offset:2112
	global_load_dwordx4 v[140:143], v174, s[48:49]
	global_load_dwordx4 v[144:147], v174, s[46:47]
	global_load_dwordx4 v[148:151], v174, s[48:49] offset:64
	global_load_dwordx4 v[152:155], v174, s[46:47] offset:64
	global_load_dwordx4 v[156:159], v174, s[48:49] offset:2048
	global_load_dwordx4 v[160:163], v174, s[46:47] offset:2048
	global_load_dwordx4 v[164:167], v174, s[48:49] offset:2112
	global_load_dwordx4 v[168:171], v174, s[46:47] offset:2112
	v_add_u32_e32 v173, 0x2000, v173
	v_add_u32_e32 v174, 0x2000, v174
	s_and_saveexec_b64 s[2:3], vcc
	s_cbranch_execz .LBB0_1006
	v_add_u32_e32 v3, -3, v0
	v_mad_u64_u32 v[4:5], s[34:35], v3, s73, v[74:75]
	global_load_dwordx4 v[60:63], v[4:5], off

; #define LAS __attribute__((address_space(3)))
; DI float silu_f(float x) { return x * __builtin_amdgcn_rcpf(1.0f + __expf(-x)); }
; DI u32x4 pack8(const float (&v)[8]) { u32x4 w; w.x = pk2(v[0], v[1]); w.y = pk2(v[2], v[3]); w.z = pk2(v[4], v[5]); w.w = pk2(v[6], v[7]); return w; }
; template <bool SILU>
; DI void conv_compute(const u32x4 (&raw)[7], const float* w, int C, const float* bias, float (&out)[4][8]) {
;     float wv[4][8], bv[8], x[7][8];
; #pragma unroll
;     for (int j = 0; j < 4; ++j) { const f32x4 a = *(const f32x4*)(w + (size_t)j * C), b = *(const f32x4*)(w + (size_t)j * C + 4);
;         wv[j][0] = a[0]; wv[j][1] = a[1]; wv[j][2] = a[2]; wv[j][3] = a[3]; wv[j][4] = b[0]; wv[j][5] = b[1]; wv[j][6] = b[2]; wv[j][7] = b[3]; }
;     { const f32x4 a = *(const f32x4*)bias, b = *(const f32x4*)(bias + 4); bv[0] = a[0]; bv[1] = a[1]; bv[2] = a[2]; bv[3] = a[3]; bv[4] = b[0]; bv[5] = b[1]; bv[6] = b[2]; bv[7] = b[3]; }
; #pragma unroll
;     for (int i = 0; i < 7; ++i) unpack8(raw[i], x[i]);
; #pragma unroll
;     for (int t = 0; t < 4; ++t)
; #pragma unroll
;         for (int c = 0; c < 8; ++c) { float v = bv[c] + wv[0][c] * x[t][c] + wv[1][c] * x[t + 1][c] + wv[2][c] * x[t + 2][c] + wv[3][c] * x[t + 3][c]; out[t][c] = SILU ? silu_f(v) : v; }
; }
; template <int MODE>
; DI void lru_chunk(LAS unsigned char* lds, const Args& a, const LayerP& P, int unit, int wv) {
;     ...
;     { const int cv = tid & 31, run = tid >> 5;
; #pragma unroll
;       for (int hf = 0; hf < 2; ++hf) { const int t0 = run * 8 + hf * 4; float o[4][8]; conv8x4<false>(Hb + C_LX + cv * 8, c * 128 + t0, P.lru_cw + cv * 8, 256, P.lru_cb + cv * 8, o);
; #pragma unroll
;           for (int t = 0; t < 4; ++t) *(LAS u32x4*)(U + (t0 + t) * PU + cv * 8) = pack8(o[t]); } }
.LBB0_1032:
	s_or_b64 exec, exec, s[2:3]
	s_waitcnt vmcnt(0)
	v_lshlrev_b32_e32 v74, 16, v42
	v_and_b32_e32 v75, 0xffff0000, v42
	v_lshlrev_b32_e32 v42, 16, v43
	v_and_b32_e32 v43, 0xffff0000, v43
	v_lshlrev_b32_e32 v76, 16, v50
	v_and_b32_e32 v77, 0xffff0000, v50
	v_lshlrev_b32_e32 v50, 16, v51
	v_and_b32_e32 v51, 0xffff0000, v51
	v_pk_fma_f32 v[42:43], v[24:25], v[42:43], v[40:41]
	v_lshlrev_b32_e32 v82, 16, v44
	v_and_b32_e32 v83, 0xffff0000, v44
	v_lshlrev_b32_e32 v78, 16, v46
	v_and_b32_e32 v79, 0xffff0000, v46
	v_lshlrev_b32_e32 v80, 16, v66
	v_and_b32_e32 v81, 0xffff0000, v66
	v_pk_fma_f32 v[74:75], v[22:23], v[74:75], v[38:39]
	v_lshlrev_b32_e32 v46, 16, v47
	v_and_b32_e32 v47, 0xffff0000, v47
	v_lshlrev_b32_e32 v66, 16, v67
	v_and_b32_e32 v67, 0xffff0000, v67
	v_pk_fma_f32 v[42:43], v[28:29], v[50:51], v[42:43]
	v_lshlrev_b32_e32 v84, 16, v52
	v_and_b32_e32 v85, 0xffff0000, v52
	v_pk_fma_f32 v[82:83], v[2:3], v[82:83], v[18:19]
	v_lshlrev_b32_e32 v44, 16, v45
	v_and_b32_e32 v45, 0xffff0000, v45
	v_pk_fma_f32 v[50:51], v[24:25], v[50:51], v[40:41]
	v_pk_fma_f32 v[74:75], v[26:27], v[76:77], v[74:75]
	v_pk_fma_f32 v[42:43], v[32:33], v[46:47], v[42:43]
	v_lshlrev_b32_e32 v86, 16, v48
	v_and_b32_e32 v87, 0xffff0000, v48
	v_lshlrev_b32_e32 v88, 16, v68
	v_and_b32_e32 v89, 0xffff0000, v68
	v_pk_fma_f32 v[82:83], v[6:7], v[84:85], v[82:83]
	v_lshlrev_b32_e32 v52, 16, v53
	v_and_b32_e32 v53, 0xffff0000, v53
	v_pk_fma_f32 v[44:45], v[4:5], v[44:45], v[20:21]
	v_lshlrev_b32_e32 v90, 16, v58
	v_and_b32_e32 v91, 0xffff0000, v58
	v_pk_fma_f32 v[76:77], v[22:23], v[76:77], v[38:39]
	v_lshlrev_b32_e32 v58, 16, v59
	v_and_b32_e32 v59, 0xffff0000, v59
	v_pk_fma_f32 v[50:51], v[28:29], v[46:47], v[50:51]
	v_pk_fma_f32 v[84:85], v[2:3], v[84:85], v[18:19]
	v_pk_fma_f32 v[46:47], v[24:25], v[46:47], v[40:41]
	v_pk_fma_f32 v[24:25], v[24:25], v[66:67], v[40:41]
	v_pk_fma_f32 v[74:75], v[30:31], v[78:79], v[74:75]
	v_pk_fma_f32 v[82:83], v[10:11], v[86:87], v[82:83]
	v_lshlrev_b32_e32 v48, 16, v49
	v_and_b32_e32 v49, 0xffff0000, v49
	v_lshlrev_b32_e32 v68, 16, v69
	v_and_b32_e32 v69, 0xffff0000, v69
	v_pk_fma_f32 v[44:45], v[8:9], v[52:53], v[44:45]
	v_pk_fma_f32 v[76:77], v[26:27], v[78:79], v[76:77]
	v_lshlrev_b32_e32 v92, 16, v60
	v_and_b32_e32 v93, 0xffff0000, v60
	v_pk_fma_f32 v[84:85], v[6:7], v[86:87], v[84:85]
	v_pk_fma_f32 v[52:53], v[4:5], v[52:53], v[20:21]
	v_lshlrev_b32_e32 v94, 16, v62
	v_and_b32_e32 v95, 0xffff0000, v62
	v_pk_fma_f32 v[78:79], v[22:23], v[78:79], v[38:39]
	v_lshlrev_b32_e32 v62, 16, v63
	v_and_b32_e32 v63, 0xffff0000, v63
	v_pk_fma_f32 v[86:87], v[2:3], v[86:87], v[18:19]
	v_pk_fma_f32 v[22:23], v[22:23], v[80:81], v[38:39]
	v_pk_fma_f32 v[24:25], v[28:29], v[58:59], v[24:25]
	v_pk_fma_f32 v[2:3], v[2:3], v[88:89], v[18:19]
	v_pk_fma_f32 v[44:45], v[12:13], v[48:49], v[44:45]
	v_lshlrev_b32_e32 v60, 16, v61
	v_and_b32_e32 v61, 0xffff0000, v61
	v_pk_fma_f32 v[52:53], v[8:9], v[48:49], v[52:53]
	v_pk_fma_f32 v[78:79], v[26:27], v[80:81], v[78:79]
	v_lshlrev_b32_e32 v96, 16, v64
	v_and_b32_e32 v97, 0xffff0000, v64
	v_pk_fma_f32 v[48:49], v[4:5], v[48:49], v[20:21]
	v_pk_fma_f32 v[22:23], v[26:27], v[90:91], v[22:23]
	v_lshlrev_b32_e32 v26, 16, v55
	v_and_b32_e32 v27, 0xffff0000, v55
	v_pk_fma_f32 v[24:25], v[32:33], v[62:63], v[24:25]
	v_pk_fma_f32 v[2:3], v[6:7], v[92:93], v[2:3]
	v_pk_fma_f32 v[4:5], v[4:5], v[68:69], v[20:21]
	v_lshlrev_b32_e32 v64, 16, v65
	v_and_b32_e32 v65, 0xffff0000, v65
	v_pk_fma_f32 v[24:25], v[36:37], v[26:27], v[24:25]
	v_lshlrev_b32_e32 v26, 16, v56
	v_and_b32_e32 v27, 0xffff0000, v56
	v_pk_fma_f32 v[2:3], v[10:11], v[96:97], v[2:3]
	v_pk_fma_f32 v[4:5], v[8:9], v[60:61], v[4:5]
	v_pk_fma_f32 v[74:75], v[34:35], v[80:81], v[74:75]
	v_pk_fma_f32 v[42:43], v[36:37], v[66:67], v[42:43]
	v_pk_fma_f32 v[82:83], v[14:15], v[88:89], v[82:83]
	v_pk_fma_f32 v[44:45], v[16:17], v[68:69], v[44:45]
	v_pk_fma_f32 v[76:77], v[30:31], v[80:81], v[76:77]
	v_pk_fma_f32 v[50:51], v[32:33], v[66:67], v[50:51]
	v_pk_fma_f32 v[84:85], v[10:11], v[88:89], v[84:85]
	v_pk_fma_f32 v[52:53], v[12:13], v[68:69], v[52:53]
	v_pk_fma_f32 v[46:47], v[28:29], v[66:67], v[46:47]
	v_pk_fma_f32 v[86:87], v[6:7], v[88:89], v[86:87]
	v_pk_fma_f32 v[48:49], v[8:9], v[68:69], v[48:49]
	v_pk_fma_f32 v[6:7], v[14:15], v[26:27], v[2:3]
	v_lshlrev_b32_e32 v2, 16, v57
	v_and_b32_e32 v3, 0xffff0000, v57
	v_pk_fma_f32 v[4:5], v[12:13], v[64:65], v[4:5]
	v_pk_fma_f32 v[76:77], v[34:35], v[90:91], v[76:77]
	v_pk_fma_f32 v[50:51], v[36:37], v[58:59], v[50:51]
	v_pk_fma_f32 v[84:85], v[14:15], v[92:93], v[84:85]
	v_pk_fma_f32 v[52:53], v[16:17], v[60:61], v[52:53]
	v_pk_fma_f32 v[78:79], v[30:31], v[90:91], v[78:79]
	v_pk_fma_f32 v[46:47], v[32:33], v[58:59], v[46:47]
	v_pk_fma_f32 v[86:87], v[10:11], v[92:93], v[86:87]
	v_pk_fma_f32 v[48:49], v[12:13], v[60:61], v[48:49]
	v_pk_fma_f32 v[8:9], v[16:17], v[2:3], v[4:5]
	v_cvt_pk_bf16_f32 v2, v74, v75
	v_cvt_pk_bf16_f32 v3, v42, v43
	v_cvt_pk_bf16_f32 v4, v82, v83
	v_cvt_pk_bf16_f32 v5, v44, v45
	v_pk_fma_f32 v[78:79], v[34:35], v[94:95], v[78:79]
	v_pk_fma_f32 v[46:47], v[36:37], v[62:63], v[46:47]
	v_pk_fma_f32 v[86:87], v[14:15], v[96:97], v[86:87]
	v_pk_fma_f32 v[48:49], v[16:17], v[64:65], v[48:49]
	ds_write_b128 v70, v[2:5] offset:2112
	v_cvt_pk_bf16_f32 v2, v76, v77
	v_cvt_pk_bf16_f32 v3, v50, v51
	v_cvt_pk_bf16_f32 v4, v84, v85
	v_cvt_pk_bf16_f32 v5, v52, v53
	ds_write_b128 v70, v[2:5] offset:2640
	v_cvt_pk_bf16_f32 v2, v78, v79
	v_cvt_pk_bf16_f32 v3, v46, v47
	v_cvt_pk_bf16_f32 v4, v86, v87
	v_cvt_pk_bf16_f32 v5, v48, v49
	ds_write_b128 v70, v[2:5] offset:3168
	v_cvt_pk_bf16_f32 v4, v6, v7
	v_or_b32_e32 v6, 7, v73
	v_mad_u64_u32 v[6:7], s[2:3], v6, s82, v[0:1]
	s_ashr_i32 s19, s18, 31
	s_lshl_b32 s16, s16, 14
	s_lshl_b64 s[2:3], s[18:19], 14
	v_lshlrev_b32_e32 v98, 16, v54
	v_and_b32_e32 v99, 0xffff0000, v54
	v_pk_fma_f32 v[22:23], v[30:31], v[94:95], v[22:23]
	s_add_u32 s94, s12, s2
	v_pk_fma_f32 v[22:23], v[34:35], v[98:99], v[22:23]
	s_addc_u32 s95, s13, s3
	s_add_i32 s29, s15, s1
	v_cvt_pk_bf16_f32 v2, v22, v23
	v_cvt_pk_bf16_f32 v3, v24, v25
	v_cvt_pk_bf16_f32 v5, v8, v9
	s_add_i32 s29, s29, s16
	s_mov_b32 s34, 0
	v_readlane_b32 s35, v254, 39
	s_mov_b32 s40, 0
	ds_write_b128 v6, v[2:5]
	s_waitcnt vmcnt(0)
	v_mov_b32_e32 v28, v175
	v_xor_b32_e32 v29, 0x80000000, v28
	v_cmp_ngt_f32_e32 vcc, s78, v28
	s_and_saveexec_b64 s[2:3], vcc
	s_cbranch_execz .Lmy_lru_sp_done
; DI float softplus_f(float x) { return x > 20.f ? x : log1pf(__expf(x)); }
; template <bool OUT>
; DI void lru_sweep(LAS bf16_t* U, LAS float* SUM, const Args& a, const LayerP& P, int row0, int wv, const float* LC, f32x2* LSWc) {
;     ...
;             const int ch = g * 64 + ni * 16 + r; const float ba = P.lru_ba[ch], bx = P.lru_bx[ch], c8 = -8.0f * softplus_f(-P.lru_ap[ch]);
	v_mul_f32_e32 v28, 0xbfb8aa3b, v28
	v_exp_f32_e32 v31, v28
	s_nop 0
	v_add_f32_e32 v32, 1.0, v31
	v_frexp_mant_f32_e32 v34, v32
	v_cvt_f64_f32_e32 v[28:29], v32
	v_frexp_exp_i32_f64_e32 v28, v[28:29]
	v_cmp_gt_f32_e32 vcc, s75, v34
	v_add_f32_e32 v33, -1.0, v32
	v_sub_f32_e32 v35, v33, v32
	v_subbrev_co_u32_e32 v37, vcc, 0, v28, vcc
	v_sub_u32_e32 v28, 0, v37
	v_sub_f32_e32 v33, v31, v33
	v_add_f32_e32 v35, 1.0, v35
	v_ldexp_f32 v29, v32, v28
	v_add_f32_e32 v33, v33, v35
	v_add_f32_e32 v32, -1.0, v29
	v_add_f32_e32 v34, 1.0, v29
	v_ldexp_f32 v28, v33, v28
	v_add_f32_e32 v33, 1.0, v32
	v_add_f32_e32 v35, -1.0, v34
	v_sub_f32_e32 v33, v29, v33
	v_sub_f32_e32 v29, v29, v35
	v_add_f32_e32 v33, v28, v33
	v_add_f32_e32 v28, v28, v29
	v_add_f32_e32 v41, v34, v28
	v_rcp_f32_e32 v43, v41
	v_sub_f32_e32 v29, v41, v34
	v_sub_f32_e32 v42, v28, v29
	v_add_f32_e32 v29, v32, v33
	v_mul_f32_e32 v45, v29, v43
	v_sub_f32_e32 v28, v29, v32
	v_mul_f32_e32 v32, v41, v45
	v_fma_f32 v34, v45, v41, -v32
	v_fmac_f32_e32 v34, v45, v42
	v_sub_f32_e32 v44, v33, v28
	v_add_f32_e32 v28, v32, v34
	v_sub_f32_e32 v33, v29, v28
	v_pk_add_f32 v[38:39], v[28:29], v[32:33] neg_lo:[0,1] neg_hi:[0,1]
	v_mov_b32_e32 v35, v28
	v_pk_add_f32 v[28:29], v[38:39], v[34:35] neg_lo:[0,1] neg_hi:[0,1]
	v_cmp_neq_f32_e32 vcc, s84, v31
	v_add_f32_e32 v29, v44, v29
	v_add_f32_e32 v28, v28, v29
	v_add_f32_e32 v29, v33, v28
	v_mul_f32_e32 v44, v43, v29
	v_mul_f32_e32 v32, v41, v44
	v_fma_f32 v34, v44, v41, -v32
	v_fmac_f32_e32 v34, v44, v42
	v_sub_f32_e32 v33, v33, v29
	v_add_f32_e32 v41, v28, v33
	v_add_f32_e32 v28, v32, v34
	v_sub_f32_e32 v33, v29, v28
	v_pk_add_f32 v[38:39], v[28:29], v[32:33] neg_lo:[0,1] neg_hi:[0,1]
	v_mov_b32_e32 v35, v28
	v_pk_add_f32 v[28:29], v[38:39], v[34:35] neg_lo:[0,1] neg_hi:[0,1]
	s_nop 0
	v_add_f32_e32 v29, v41, v29
	v_add_f32_e32 v28, v28, v29
	v_add_f32_e32 v29, v45, v44
	v_add_f32_e32 v28, v33, v28
	v_sub_f32_e32 v32, v29, v45
	v_mul_f32_e32 v28, v43, v28
	v_sub_f32_e32 v32, v44, v32
	v_add_f32_e32 v32, v32, v28
	v_add_f32_e32 v34, v29, v32
	v_mul_f32_e32 v35, v34, v34
	v_fmamk_f32 v28, v35, 0x3e9b6dac, v203
	v_fmaak_f32 v189, v35, v28, 0x3f2aaada
	v_cvt_f32_i32_e32 v28, v37
	v_sub_f32_e32 v29, v34, v29
	v_sub_f32_e32 v29, v32, v29
	v_ldexp_f32 v37, v29, 1
	v_mul_f32_e32 v29, v34, v35
	v_ldexp_f32 v33, v34, 1
	v_pk_mul_f32 v[34:35], v[28:29], v[188:189]
	s_nop 0
	v_fma_f32 v32, v28, s31, -v34
	v_fmac_f32_e32 v32, 0xb102e308, v28
	v_pk_add_f32 v[28:29], v[34:35], v[32:33]
	v_mov_b32_e32 v38, v34
	v_sub_f32_e32 v33, v29, v33
	v_sub_f32_e32 v33, v35, v33
	v_add_f32_e32 v39, v37, v33
	v_pk_add_f32 v[34:35], v[28:29], v[34:35] neg_lo:[0,1] neg_hi:[0,1]
	v_pk_add_f32 v[42:43], v[28:29], v[38:39]
	v_mov_b32_e32 v33, v28
	v_mov_b32_e32 v35, v43
	v_pk_add_f32 v[44:45], v[32:33], v[34:35] neg_lo:[0,1] neg_hi:[0,1]
	v_pk_add_f32 v[32:33], v[32:33], v[34:35]
	v_mov_b32_e32 v38, v39
	v_pk_add_f32 v[34:35], v[32:33], v[28:29] op_sel:[1,0] op_sel_hi:[0,1] neg_lo:[0,1] neg_hi:[0,1]
	v_pk_add_f32 v[46:47], v[42:43], v[34:35] op_sel_hi:[1,0] neg_lo:[0,1] neg_hi:[0,1]
	v_mov_b32_e32 v42, v43
	v_mov_b32_e32 v43, v33
	v_pk_mov_b32 v[34:35], v[28:29], v[34:35] op_sel:[1,0]
	v_mov_b32_e32 v39, v28
	v_pk_add_f32 v[34:35], v[42:43], v[34:35] neg_lo:[0,1] neg_hi:[0,1]
	v_mov_b32_e32 v46, v44
	v_pk_add_f32 v[28:29], v[38:39], v[34:35] neg_lo:[0,1] neg_hi:[0,1]
	v_mov_b32_e32 v45, v33
	v_pk_add_f32 v[34:35], v[46:47], v[28:29]
	s_nop 0
	v_pk_add_f32 v[38:39], v[34:35], v[34:35] op_sel:[0,1] op_sel_hi:[1,0]
	s_nop 0
	v_pk_add_f32 v[32:33], v[32:33], v[38:39] op_sel:[1,0] op_sel_hi:[0,1]
	v_mov_b32_e32 v35, v32
	v_pk_add_f32 v[42:43], v[34:35], v[44:45] neg_lo:[0,1] neg_hi:[0,1]
	v_mov_b32_e32 v29, v38
	v_sub_f32_e32 v33, v34, v42
	v_pk_add_f32 v[28:29], v[28:29], v[42:43] neg_lo:[0,1] neg_hi:[0,1]
	v_sub_f32_e32 v33, v44, v33
	v_add_f32_e32 v28, v28, v33
	v_add_f32_e32 v28, v28, v29
	v_add_f32_e32 v28, v32, v28
	v_cndmask_b32_e32 v28, v206, v28, vcc
	v_cmp_ngt_f32_e32 vcc, -1.0, v31
	s_nop 1
	v_cndmask_b32_e32 v28, v207, v28, vcc
	v_cmp_neq_f32_e32 vcc, -1.0, v31
	s_nop 1
	v_cndmask_b32_e32 v28, v208, v28, vcc
	v_cmp_lt_f32_e64 vcc, |v31|, s85
	s_nop 1
	v_cndmask_b32_e32 v29, v28, v31, vcc
.Lmy_lru_sp_done:
	s_or_b64 exec, exec, s[2:3]
	v_mul_f32_e32 v29, 0xc1000000, v29
	v_add_u32_e32 v178, 0x14800, v178
	ds_write_b32 v178, v29
	ds_write_b32 v178, v176 offset:1024
	ds_write_b32 v178, v177 offset:2048
	s_waitcnt lgkmcnt(0)
	s_barrier
	s_branch .LBB0_1034

; __device__ __forceinline__ int ltid(int wv) { int l; asm volatile("v_mbcnt_lo_u32_b32 %0, -1, 0\n\tv_mbcnt_hi_u32_b32 %0, -1, %0" : "=v"(l)); asm volatile("" : "+s"(wv)); return (wv << 6) | l; }
; #define LAS __attribute__((address_space(3)))
; DI float bf2f(unsigned short u) { return __uint_as_float((unsigned)u << 16); }
; DI float sigmoid_f(float x) { return __builtin_amdgcn_rcpf(1.0f + __expf(-x)); }
; DI float softplus_f(float x) { return x > 20.f ? x : log1pf(__expf(x)); }
; DI float one_minus_exp(float x) { const float p = -x * (1.0f + x * (0.5f + x * (0.16666667f + x * (0.041666668f + x * 0.008333334f)))); if (__builtin_expect(__any(x <= -0.5f), 0)) return x > -0.5f ? p : 1.0f - __expf(x); return p; }
; template <bool OUT>
; DI void lru_sweep(LAS bf16_t* U, LAS float* SUM, const Args& a, const LayerP& P, int row0, int wv, const float* LC, f32x2* LSWc) {
;     ...
;         const int lane = ltid(wv) & 63, r = lane & 15, q = lane >> 4;
;         bf16x8 af[2];
; #pragma unroll
;         for (int ks = 0; ks < 2; ++ks) af[ks] = *(const LAS bf16x8*)(U + (l0 + r) * PU + g * 64 + ks * 32 + q * 8);
; #pragma unroll
;         for (int ni = 0; ni < 4; ++ni) { f32x4 aa1 = (f32x4){0.f, 0.f, 0.f, 0.f}, ax1 = aa1;
; #pragma unroll
;             for (int ks = 0; ks < 2; ++ks) { const bf16x8 wa = *(const bf16x8*)(LWT + ((size_t)(g * 64 + ni * 16 + r)) * 64 + ks * 32 + q * 8), wx = *(const bf16x8*)(LWT + ((size_t)((4 + g) * 64 + ni * 16 + r)) * 64 + ks * 32 + q * 8);
;                 aa1 = __builtin_amdgcn_mfma_f32_16x16x32_bf16(af[ks], wa, aa1, 0, 0, 0); ax1 = __builtin_amdgcn_mfma_f32_16x16x32_bf16(af[ks], wx, ax1, 0, 0, 0); }
;             const int ch = g * 64 + ni * 16 + r; const float ba = P.lru_ba[ch], bx = P.lru_bx[ch], c8 = -8.0f * softplus_f(-P.lru_ap[ch]);
;             float Pi[4], Ei[4], Pc = 1.f, Ec = 0.f;
; #pragma unroll
;             for (int j = 0; j < 4; ++j) { const float rg = sigmoid_f(aa1[j] + ba), ig = sigmoid_f(ax1[j] + bx); const float la = c8 * rg, av = __expf(la);
;                 const float u = bf2f(U[(l0 + 4 * q + j) * PU + ch]); const float inp = __builtin_amdgcn_sqrtf(one_minus_exp(2.0f * la)) * (ig * u);
.LBB0_1034:
	s_waitcnt lgkmcnt(4)
	v_mbcnt_lo_u32_b32 v0, -1, 0
	v_mbcnt_hi_u32_b32 v0, -1, v0
	s_mov_b32 s2, s77
	v_and_b32_e32 v40, 15, v0
	v_add_u32_e32 v172, s40, v40
	v_lshlrev_b32_e32 v172, 2, v172
	v_add_u32_e32 v172, 0x14800, v172
	v_bfe_u32 v36, v0, 4, 2
	v_lshl_add_u32 v24, v40, 6, s34
	v_mov_b32_e32 v25, v1
	v_lshlrev_b32_e32 v0, 4, v36
	v_lshl_add_u64 v[10:11], v[24:25], 1, s[48:49]
	v_lshl_add_u64 v[26:27], v[10:11], 0, v[0:1]
	s_mov_b32 s2, 0x8000
	s_waitcnt lgkmcnt(2)
	v_mul_u32_u24_e32 v2, 0x210, v40
	v_add_co_u32_e32 v14, vcc, s2, v26
	v_add3_u32 v2, v2, v0, s35
	s_nop 0
	v_addc_co_u32_e32 v15, vcc, 0, v27, vcc
	s_waitcnt lgkmcnt(0)
	ds_read_b32 v179, v172
	ds_read_b32 v180, v172 offset:1024
	ds_read_b32 v181, v172 offset:2048
	ds_read_b128 v[6:9], v2
	ds_read_b128 v[2:5], v2 offset:64
	v_lshl_add_u64 v[22:23], v[26:27], 0, s[52:53]
	v_add_u32_e32 v32, s40, v40
	v_mov_b32_e32 v0, v32
	s_waitcnt vmcnt(32) lgkmcnt(1)
	v_mfma_f32_16x16x32_bf16 v[10:13], v[6:9], v[108:111], 0
	v_mfma_f32_16x16x32_bf16 v[18:21], v[6:9], v[112:115], 0
	v_lshlrev_b64 v[22:23], 2, v[0:1]
	s_waitcnt lgkmcnt(0)
	v_mfma_f32_16x16x32_bf16 v[14:17], v[2:5], v[116:119], v[10:13]
	v_mfma_f32_16x16x32_bf16 v[10:13], v[2:5], v[120:123], v[18:21]
	s_nop 2
	v_lshl_add_u64 v[18:19], s[26:27], 0, v[22:23]
	v_lshl_add_u64 v[20:21], s[36:37], 0, v[22:23]
	v_lshl_add_u64 v[22:23], s[38:39], 0, v[22:23]
	s_cmpk_eq_i32 s40, 0xc0
	s_cbranch_scc1 .Lmy_lru_nopf0
	global_load_dwordx4 v[108:111], v173, s[48:49]
	global_load_dwordx4 v[112:115], v173, s[46:47]
	global_load_dwordx4 v[116:119], v173, s[48:49] offset:64
	global_load_dwordx4 v[120:123], v173, s[46:47] offset:64
.Lmy_lru_nopf0:
	s_nop 7
	v_mov_b32_e32 v37, v179
	v_mov_b32_e32 v30, v180
	v_mov_b32_e32 v25, v181
	v_add_f32_e32 v14, v14, v30
	v_mul_f32_e32 v14, 0xbfb8aa3b, v14
	v_exp_f32_e32 v28, v14
	v_lshlrev_b32_e32 v14, 2, v36
	s_nop 0
	v_or_b32_e32 v31, s1, v14
	v_add_f32_e32 v28, 1.0, v28
	v_rcp_f32_e32 v28, v28
	v_lshl_add_u32 v29, v0, 1, 0
	v_mul_lo_u32 v31, v31, s82
	v_add_u32_e32 v41, v29, v31
	v_mul_f32_e32 v33, v28, v37
	v_add_f32_e32 v31, v33, v33
	ds_read_u16 v28, v41
	v_fmamk_f32 v29, v31, 0x3c088889, v204
	v_fmaak_f32 v29, v31, v29, 0x3e2aaaab
	v_fma_f32 v29, v31, v29, 0.5
	v_fma_f32 v29, v31, v29, 1.0
	v_mul_f32_e64 v29, v29, -v31
	v_cmp_ge_f32_e32 vcc, -0.5, v31
	s_cbranch_vccnz .LBB0_1082

; DI float bf2f(unsigned short u) { return __uint_as_float((unsigned)u << 16); }
; DI unsigned pk2(float lo, float hi) { const f32x2 v = {lo, hi}; const hwbf16x2 b = __builtin_convertvector(v, hwbf16x2); return __builtin_bit_cast(unsigned, b); }
; DI float sigmoid_f(float x) { return __builtin_amdgcn_rcpf(1.0f + __expf(-x)); }
; DI float one_minus_exp(float x) { const float p = -x * (1.0f + x * (0.5f + x * (0.16666667f + x * (0.041666668f + x * 0.008333334f)))); if (__builtin_expect(__any(x <= -0.5f), 0)) return x > -0.5f ? p : 1.0f - __expf(x); return p; }
; template <bool OUT>
; DI void lru_sweep(LAS bf16_t* U, LAS float* SUM, const Args& a, const LayerP& P, int row0, int wv, const float* LC, f32x2* LSWc) {
;     ...
;             for (int j = 0; j < 4; ++j) { const float rg = sigmoid_f(aa1[j] + ba), ig = sigmoid_f(ax1[j] + bx); const float la = c8 * rg, av = __expf(la);
;                 const float u = bf2f(U[(l0 + 4 * q + j) * PU + ch]); const float inp = __builtin_amdgcn_sqrtf(one_minus_exp(2.0f * la)) * (ig * u);
;                 if (!OUT) ((unsigned*)(a.ws + WS_LA))[(size_t)(row0 + l0 + 4 * q + j) * 256 + ch] = pk2(one_minus_exp(la), inp);
;                 Ec = av * Ec + inp; Pc = Pc * av; Pi[j] = Pc; Ei[j] = Ec; }
.LBB0_1038:
	v_add_f32_e32 v10, v10, v25
	v_mul_f32_e32 v10, 0xbfb8aa3b, v10
	v_exp_f32_e32 v10, v10
	v_add_f32_e32 v15, v15, v30
	v_mul_f32_e32 v15, 0xbfb8aa3b, v15
	v_exp_f32_e32 v33, v15
	v_add_f32_e32 v10, 1.0, v10
	v_rcp_f32_e32 v10, v10
	s_waitcnt lgkmcnt(0)
	v_lshlrev_b32_e32 v28, 16, v28
	v_sqrt_f32_e32 v29, v29
	v_or_b32_e32 v14, s29, v14
	v_mul_f32_e32 v10, v10, v28
	v_add_f32_e32 v28, 1.0, v33
	v_rcp_f32_e32 v39, v28
	v_ashrrev_i32_e32 v15, 31, v14
	v_lshl_add_u64 v[34:35], v[0:1], 2, s[50:51]
	v_mul_f32_e32 v10, v10, v29
	v_lshlrev_b64 v[28:29], 10, v[14:15]
	v_mul_f32_e32 v39, v39, v37
	v_cvt_pk_bf16_f32 v38, v32, v10
	v_lshl_add_u64 v[32:33], v[34:35], 0, v[28:29]
	v_add_f32_e32 v15, v39, v39
	global_store_dword v[32:33], v38, off
	ds_read_u16 v32, v41 offset:528
	v_fmamk_f32 v33, v15, 0x3c088889, v204
	v_fmaak_f32 v33, v15, v33, 0x3e2aaaab
	v_fma_f32 v33, v15, v33, 0.5
	v_fma_f32 v33, v15, v33, 1.0
	v_mul_f32_e64 v33, v33, -v15
	v_cmp_ge_f32_e32 vcc, -0.5, v15
	s_cbranch_vccnz .LBB0_1088

; DI float bf2f(unsigned short u) { return __uint_as_float((unsigned)u << 16); }
; DI float sigmoid_f(float x) { return __builtin_amdgcn_rcpf(1.0f + __expf(-x)); }
; DI float softplus_f(float x) { return x > 20.f ? x : log1pf(__expf(x)); }
; DI float one_minus_exp(float x) { const float p = -x * (1.0f + x * (0.5f + x * (0.16666667f + x * (0.041666668f + x * 0.008333334f)))); if (__builtin_expect(__any(x <= -0.5f), 0)) return x > -0.5f ? p : 1.0f - __expf(x); return p; }
; template <bool OUT>
; DI void lru_sweep(LAS bf16_t* U, LAS float* SUM, const Args& a, const LayerP& P, int row0, int wv, const float* LC, f32x2* LSWc) {
;     ...
;         for (int ni = 0; ni < 4; ++ni) { f32x4 aa1 = (f32x4){0.f, 0.f, 0.f, 0.f}, ax1 = aa1;
; #pragma unroll
;             for (int ks = 0; ks < 2; ++ks) { const bf16x8 wa = *(const bf16x8*)(LWT + ((size_t)(g * 64 + ni * 16 + r)) * 64 + ks * 32 + q * 8), wx = *(const bf16x8*)(LWT + ((size_t)((4 + g) * 64 + ni * 16 + r)) * 64 + ks * 32 + q * 8);
;                 aa1 = __builtin_amdgcn_mfma_f32_16x16x32_bf16(af[ks], wa, aa1, 0, 0, 0); ax1 = __builtin_amdgcn_mfma_f32_16x16x32_bf16(af[ks], wx, ax1, 0, 0, 0); }
;             const int ch = g * 64 + ni * 16 + r; const float ba = P.lru_ba[ch], bx = P.lru_bx[ch], c8 = -8.0f * softplus_f(-P.lru_ap[ch]);
;             float Pi[4], Ei[4], Pc = 1.f, Ec = 0.f;
; #pragma unroll
;             for (int j = 0; j < 4; ++j) { const float rg = sigmoid_f(aa1[j] + ba), ig = sigmoid_f(ax1[j] + bx); const float la = c8 * rg, av = __expf(la);
;                 const float u = bf2f(U[(l0 + 4 * q + j) * PU + ch]); const float inp = __builtin_amdgcn_sqrtf(one_minus_exp(2.0f * la)) * (ig * u);
.LBB0_1046:
	s_or_b64 exec, exec, s[2:3]
	ds_read_b32 v179, v172 offset:64
	ds_read_b32 v180, v172 offset:1088
	ds_read_b32 v181, v172 offset:2112
	s_waitcnt lgkmcnt(1)
	s_waitcnt lgkmcnt(0)
	v_lshlrev_b32_e32 v34, 3, v36
	v_ashrrev_i32_e32 v25, 31, v24
	v_mov_b32_e32 v35, v1
	v_lshl_add_u64 v[36:37], v[24:25], 1, s[48:49]
	v_lshlrev_b32_e32 v34, 1, v34
	v_lshl_add_u64 v[24:25], v[36:37], 0, v[34:35]
	v_add_co_u32_e32 v26, vcc, 0x8000, v24
	s_mov_b64 s[2:3], 0x8800
	s_nop 0
	v_addc_co_u32_e32 v27, vcc, 0, v25, vcc
	v_lshl_add_u64 v[24:25], v[24:25], 0, s[2:3]
	s_waitcnt vmcnt(28)
	v_mfma_f32_16x16x32_bf16 v[10:13], v[6:9], v[124:127], 0
	v_mfma_f32_16x16x32_bf16 v[14:17], v[2:5], v[132:135], v[10:13]
	s_nop 5
	s_nop 0
	v_mfma_f32_16x16x32_bf16 v[44:47], v[6:9], v[128:131], 0
	v_mfma_f32_16x16x32_bf16 v[10:13], v[2:5], v[136:139], v[44:47]
	s_cmpk_eq_i32 s40, 0xc0
	s_cbranch_scc1 .Lmy_lru_nopf1
	global_load_dwordx4 v[124:127], v173, s[48:49] offset:2048
	global_load_dwordx4 v[128:131], v173, s[46:47] offset:2048
	global_load_dwordx4 v[132:135], v173, s[48:49] offset:2112
	global_load_dwordx4 v[136:139], v173, s[46:47] offset:2112
.Lmy_lru_nopf1:
	s_nop 7
	v_mov_b32_e32 v45, v179
	v_mov_b32_e32 v43, v180
	v_mov_b32_e32 v35, v181
	v_add_f32_e32 v14, v14, v43
	v_mul_f32_e32 v14, 0xbfb8aa3b, v14
	v_exp_f32_e32 v14, v14
	s_nop 0
	v_add_f32_e32 v14, 1.0, v14
	v_rcp_f32_e32 v25, v14
	ds_read_u16 v14, v41 offset:32
	v_mul_f32_e32 v25, v25, v45
	v_add_f32_e32 v26, v25, v25
	v_fmamk_f32 v24, v26, 0x3c088889, v204
	v_fmaak_f32 v24, v26, v24, 0x3e2aaaab
	v_fma_f32 v24, v26, v24, 0.5
	v_fma_f32 v24, v26, v24, 1.0
	v_cmp_ge_f32_e32 vcc, -0.5, v26
	v_mul_f32_e64 v24, v24, -v26
	s_cbranch_vccnz .LBB0_1106

; DI float bf2f(unsigned short u) { return __uint_as_float((unsigned)u << 16); }
; DI unsigned pk2(float lo, float hi) { const f32x2 v = {lo, hi}; const hwbf16x2 b = __builtin_convertvector(v, hwbf16x2); return __builtin_bit_cast(unsigned, b); }
; DI float sigmoid_f(float x) { return __builtin_amdgcn_rcpf(1.0f + __expf(-x)); }
; DI float one_minus_exp(float x) { const float p = -x * (1.0f + x * (0.5f + x * (0.16666667f + x * (0.041666668f + x * 0.008333334f)))); if (__builtin_expect(__any(x <= -0.5f), 0)) return x > -0.5f ? p : 1.0f - __expf(x); return p; }
; template <bool OUT>
; DI void lru_sweep(LAS bf16_t* U, LAS float* SUM, const Args& a, const LayerP& P, int row0, int wv, const float* LC, f32x2* LSWc) {
;     ...
;             for (int j = 0; j < 4; ++j) { const float rg = sigmoid_f(aa1[j] + ba), ig = sigmoid_f(ax1[j] + bx); const float la = c8 * rg, av = __expf(la);
;                 const float u = bf2f(U[(l0 + 4 * q + j) * PU + ch]); const float inp = __builtin_amdgcn_sqrtf(one_minus_exp(2.0f * la)) * (ig * u);
;                 if (!OUT) ((unsigned*)(a.ws + WS_LA))[(size_t)(row0 + l0 + 4 * q + j) * 256 + ch] = pk2(one_minus_exp(la), inp);
;                 Ec = av * Ec + inp; Pc = Pc * av; Pi[j] = Pc; Ei[j] = Ec; }
.LBB0_1050:
	v_add_f32_e32 v10, v10, v35
	v_mul_f32_e32 v10, 0xbfb8aa3b, v10
	v_exp_f32_e32 v10, v10
	v_add_f32_e32 v15, v15, v43
	v_mul_f32_e32 v15, 0xbfb8aa3b, v15
	v_sqrt_f32_e32 v24, v24
	v_add_f32_e32 v10, 1.0, v10
	v_rcp_f32_e32 v10, v10
	v_exp_f32_e32 v27, v15
	s_waitcnt lgkmcnt(0)
	v_lshlrev_b32_e32 v25, 16, v14
	v_add_u32_e32 v14, 16, v0
	v_mul_f32_e32 v10, v10, v25
	v_mul_f32_e32 v10, v10, v24
	v_add_f32_e32 v24, 1.0, v27
	v_rcp_f32_e32 v47, v24
	v_mov_b32_e32 v15, v1
	v_lshl_add_u64 v[24:25], s[50:51], 0, v[28:29]
	v_cvt_pk_bf16_f32 v46, v26, v10
	v_mul_f32_e32 v29, v47, v45
	v_lshl_add_u64 v[26:27], v[14:15], 2, v[24:25]
	v_add_f32_e32 v28, v29, v29
	global_store_dword v[26:27], v46, off
	ds_read_u16 v26, v41 offset:560
	v_fmamk_f32 v27, v28, 0x3c088889, v204
	v_fmaak_f32 v27, v28, v27, 0x3e2aaaab
	v_fma_f32 v27, v28, v27, 0.5
	v_fma_f32 v27, v28, v27, 1.0
	v_mul_f32_e64 v27, v27, -v28
	v_cmp_ge_f32_e32 vcc, -0.5, v28
	s_cbranch_vccnz .LBB0_1112

; DI float bf2f(unsigned short u) { return __uint_as_float((unsigned)u << 16); }
; DI float sigmoid_f(float x) { return __builtin_amdgcn_rcpf(1.0f + __expf(-x)); }
; DI float softplus_f(float x) { return x > 20.f ? x : log1pf(__expf(x)); }
; DI float one_minus_exp(float x) { const float p = -x * (1.0f + x * (0.5f + x * (0.16666667f + x * (0.041666668f + x * 0.008333334f)))); if (__builtin_expect(__any(x <= -0.5f), 0)) return x > -0.5f ? p : 1.0f - __expf(x); return p; }
; template <bool OUT>
; DI void lru_sweep(LAS bf16_t* U, LAS float* SUM, const Args& a, const LayerP& P, int row0, int wv, const float* LC, f32x2* LSWc) {
;     ...
;         for (int ni = 0; ni < 4; ++ni) { f32x4 aa1 = (f32x4){0.f, 0.f, 0.f, 0.f}, ax1 = aa1;
; #pragma unroll
;             for (int ks = 0; ks < 2; ++ks) { const bf16x8 wa = *(const bf16x8*)(LWT + ((size_t)(g * 64 + ni * 16 + r)) * 64 + ks * 32 + q * 8), wx = *(const bf16x8*)(LWT + ((size_t)((4 + g) * 64 + ni * 16 + r)) * 64 + ks * 32 + q * 8);
;                 aa1 = __builtin_amdgcn_mfma_f32_16x16x32_bf16(af[ks], wa, aa1, 0, 0, 0); ax1 = __builtin_amdgcn_mfma_f32_16x16x32_bf16(af[ks], wx, ax1, 0, 0, 0); }
;             const int ch = g * 64 + ni * 16 + r; const float ba = P.lru_ba[ch], bx = P.lru_bx[ch], c8 = -8.0f * softplus_f(-P.lru_ap[ch]);
;             float Pi[4], Ei[4], Pc = 1.f, Ec = 0.f;
; #pragma unroll
;             for (int j = 0; j < 4; ++j) { const float rg = sigmoid_f(aa1[j] + ba), ig = sigmoid_f(ax1[j] + bx); const float la = c8 * rg, av = __expf(la);
;                 const float u = bf2f(U[(l0 + 4 * q + j) * PU + ch]); const float inp = __builtin_amdgcn_sqrtf(one_minus_exp(2.0f * la)) * (ig * u);
.LBB0_1058:
	s_or_b64 exec, exec, s[2:3]
	ds_read_b32 v179, v172 offset:128
	ds_read_b32 v180, v172 offset:1152
	ds_read_b32 v181, v172 offset:2176
	v_mov_b32_e32 v35, v1
	s_waitcnt lgkmcnt(2)
	v_lshl_add_u64 v[14:15], v[36:37], 0, v[34:35]
	s_mov_b64 s[2:3], 0x1000
	v_add_co_u32_e32 v10, vcc, 0x1000, v14
	v_lshl_add_u64 v[48:49], v[14:15], 0, s[2:3]
	s_mov_b64 s[2:3], 0x9000
	v_addc_co_u32_e32 v11, vcc, 0, v15, vcc
	v_lshl_add_u64 v[50:51], v[14:15], 0, s[2:3]
	v_add_co_u32_e32 v14, vcc, 0x9000, v14
	s_waitcnt lgkmcnt(1)
	v_addc_co_u32_e32 v15, vcc, 0, v15, vcc
	s_waitcnt lgkmcnt(0)
	s_waitcnt vmcnt(24)
	v_mfma_f32_16x16x32_bf16 v[10:13], v[6:9], v[140:143], 0
	v_mfma_f32_16x16x32_bf16 v[44:47], v[6:9], v[144:147], 0
	s_nop 0
	s_nop 0
	v_mfma_f32_16x16x32_bf16 v[14:17], v[2:5], v[148:151], v[10:13]
	v_mfma_f32_16x16x32_bf16 v[10:13], v[2:5], v[152:155], v[44:47]
	s_nop 2
	s_cmpk_eq_i32 s40, 0xc0
	s_cbranch_scc1 .Lmy_lru_nopf2
	global_load_dwordx4 v[140:143], v174, s[48:49]
	global_load_dwordx4 v[144:147], v174, s[46:47]
	global_load_dwordx4 v[148:151], v174, s[48:49] offset:64
	global_load_dwordx4 v[152:155], v174, s[46:47] offset:64
.Lmy_lru_nopf2:
	s_nop 7
	v_mov_b32_e32 v44, v179
	v_mov_b32_e32 v35, v180
	v_mov_b32_e32 v31, v181
	v_add_f32_e32 v14, v14, v35
	v_mul_f32_e32 v14, 0xbfb8aa3b, v14
	v_exp_f32_e32 v14, v14
	s_nop 0
	v_add_f32_e32 v14, 1.0, v14
	v_rcp_f32_e32 v43, v14
	ds_read_u16 v14, v41 offset:64
	v_mul_f32_e32 v47, v43, v44
	v_add_f32_e32 v43, v47, v47
	v_fmamk_f32 v45, v43, 0x3c088889, v204
	v_fmaak_f32 v45, v43, v45, 0x3e2aaaab
	v_fma_f32 v45, v43, v45, 0.5
	v_fma_f32 v45, v43, v45, 1.0
	v_cmp_ge_f32_e32 vcc, -0.5, v43
	v_mul_f32_e64 v45, v45, -v43
	s_cbranch_vccnz .LBB0_1130

; DI float bf2f(unsigned short u) { return __uint_as_float((unsigned)u << 16); }
; DI float sigmoid_f(float x) { return __builtin_amdgcn_rcpf(1.0f + __expf(-x)); }
; DI float softplus_f(float x) { return x > 20.f ? x : log1pf(__expf(x)); }
; DI float one_minus_exp(float x) { const float p = -x * (1.0f + x * (0.5f + x * (0.16666667f + x * (0.041666668f + x * 0.008333334f)))); if (__builtin_expect(__any(x <= -0.5f), 0)) return x > -0.5f ? p : 1.0f - __expf(x); return p; }
; template <bool OUT>
; DI void lru_sweep(LAS bf16_t* U, LAS float* SUM, const Args& a, const LayerP& P, int row0, int wv, const float* LC, f32x2* LSWc) {
;     ...
;         for (int ni = 0; ni < 4; ++ni) { f32x4 aa1 = (f32x4){0.f, 0.f, 0.f, 0.f}, ax1 = aa1;
; #pragma unroll
;             for (int ks = 0; ks < 2; ++ks) { const bf16x8 wa = *(const bf16x8*)(LWT + ((size_t)(g * 64 + ni * 16 + r)) * 64 + ks * 32 + q * 8), wx = *(const bf16x8*)(LWT + ((size_t)((4 + g) * 64 + ni * 16 + r)) * 64 + ks * 32 + q * 8);
;                 aa1 = __builtin_amdgcn_mfma_f32_16x16x32_bf16(af[ks], wa, aa1, 0, 0, 0); ax1 = __builtin_amdgcn_mfma_f32_16x16x32_bf16(af[ks], wx, ax1, 0, 0, 0); }
;             const int ch = g * 64 + ni * 16 + r; const float ba = P.lru_ba[ch], bx = P.lru_bx[ch], c8 = -8.0f * softplus_f(-P.lru_ap[ch]);
;             float Pi[4], Ei[4], Pc = 1.f, Ec = 0.f;
; #pragma unroll
;             for (int j = 0; j < 4; ++j) { const float rg = sigmoid_f(aa1[j] + ba), ig = sigmoid_f(ax1[j] + bx); const float la = c8 * rg, av = __expf(la);
;                 const float u = bf2f(U[(l0 + 4 * q + j) * PU + ch]); const float inp = __builtin_amdgcn_sqrtf(one_minus_exp(2.0f * la)) * (ig * u);
.LBB0_1070:
	s_or_b64 exec, exec, s[2:3]
	ds_read_b32 v179, v172 offset:192
	ds_read_b32 v180, v172 offset:1216
	ds_read_b32 v181, v172 offset:2240
	v_mov_b32_e32 v35, v1
	s_waitcnt lgkmcnt(2)
	v_lshl_add_u64 v[14:15], v[36:37], 0, v[34:35]
	v_add_co_u32_e32 v10, vcc, 0x1000, v14
	s_mov_b64 s[2:3], 0x9800
	s_nop 0
	v_addc_co_u32_e32 v11, vcc, 0, v15, vcc
	v_lshl_add_u64 v[34:35], v[14:15], 0, s[64:65]
	v_lshl_add_u64 v[36:37], v[14:15], 0, s[2:3]
	v_add_co_u32_e32 v14, vcc, 0x9000, v14
	s_waitcnt lgkmcnt(1)
	v_addc_co_u32_e32 v15, vcc, 0, v15, vcc
	s_waitcnt lgkmcnt(0)
	s_waitcnt vmcnt(20)
	v_mfma_f32_16x16x32_bf16 v[10:13], v[6:9], v[156:159], 0
	v_mfma_f32_16x16x32_bf16 v[14:17], v[6:9], v[160:163], 0
	s_nop 0
	v_mfma_f32_16x16x32_bf16 v[6:9], v[2:5], v[164:167], v[10:13]
	s_nop 2
	v_mfma_f32_16x16x32_bf16 v[2:5], v[2:5], v[168:171], v[14:17]
	s_cmpk_eq_i32 s40, 0xc0
	s_cbranch_scc1 .Lmy_lru_nopf3
	global_load_dwordx4 v[156:159], v174, s[48:49] offset:2048
	global_load_dwordx4 v[160:163], v174, s[46:47] offset:2048
	global_load_dwordx4 v[164:167], v174, s[48:49] offset:2112
	global_load_dwordx4 v[168:171], v174, s[46:47] offset:2112
	v_add_u32_e32 v173, 0x2000, v173
	v_add_u32_e32 v174, 0x2000, v174
.Lmy_lru_nopf3:
	s_nop 7
	v_mov_b32_e32 v12, v179
	v_mov_b32_e32 v11, v180
	v_mov_b32_e32 v10, v181
	v_add_f32_e32 v6, v6, v11
	v_mul_f32_e32 v6, 0xbfb8aa3b, v6
	v_exp_f32_e32 v6, v6
	s_nop 0
	ds_read_u16 v13, v41 offset:96
	v_add_f32_e32 v6, 1.0, v6
	v_rcp_f32_e32 v6, v6
	s_nop 0
	v_mul_f32_e32 v16, v6, v12
	v_add_f32_e32 v6, v16, v16
	v_fmamk_f32 v14, v6, 0x3c088889, v204
	v_fmaak_f32 v14, v6, v14, 0x3e2aaaab
	v_fma_f32 v14, v6, v14, 0.5
	v_fma_f32 v14, v6, v14, 1.0
	v_cmp_ge_f32_e32 vcc, -0.5, v6
	v_mul_f32_e64 v14, v14, -v6
	s_cbranch_vccnz .LBB0_1154
